# PEER U loop: activation piece requested first in each half; single vmcnt(17) turned into a counted ladder vmcnt(32..17) per gathered row
# speedup vs baseline: 1.0049x; 1.0049x over previous
.LBB0_1375:
	v_max_u32_dpp v31, v72, v72 row_ror:1 row_mask:0xf bank_mask:0xf bound_ctrl:1
	v_max_u32_dpp v30, v76, v76 row_ror:1 row_mask:0xf bank_mask:0xf bound_ctrl:1
	v_max_u32_dpp v32, v80, v80 row_ror:1 row_mask:0xf bank_mask:0xf bound_ctrl:1
	v_max_u32_dpp v31, v31, v31 row_ror:2 row_mask:0xf bank_mask:0xf bound_ctrl:1
	v_max_u32_dpp v33, v84, v84 row_ror:1 row_mask:0xf bank_mask:0xf bound_ctrl:1
	v_max_u32_dpp v30, v30, v30 row_ror:2 row_mask:0xf bank_mask:0xf bound_ctrl:1
	v_max_u32_dpp v32, v32, v32 row_ror:2 row_mask:0xf bank_mask:0xf bound_ctrl:1
	v_max_u32_dpp v31, v31, v31 row_ror:4 row_mask:0xf bank_mask:0xf bound_ctrl:1
	v_max_u32_dpp v33, v33, v33 row_ror:2 row_mask:0xf bank_mask:0xf bound_ctrl:1
	v_max_u32_dpp v30, v30, v30 row_ror:4 row_mask:0xf bank_mask:0xf bound_ctrl:1
	v_max_u32_dpp v32, v32, v32 row_ror:4 row_mask:0xf bank_mask:0xf bound_ctrl:1
	v_max_u32_dpp v31, v31, v31 row_ror:8 row_mask:0xf bank_mask:0xf bound_ctrl:1
	v_max_u32_dpp v33, v33, v33 row_ror:4 row_mask:0xf bank_mask:0xf bound_ctrl:1
	v_max_u32_dpp v30, v30, v30 row_ror:8 row_mask:0xf bank_mask:0xf bound_ctrl:1
	v_max_u32_dpp v32, v32, v32 row_ror:8 row_mask:0xf bank_mask:0xf bound_ctrl:1
	v_max_u32_dpp v33, v33, v33 row_ror:8 row_mask:0xf bank_mask:0xf bound_ctrl:1
	v_cmp_eq_u32_e64 s[84:85], v72, v31
	v_cmp_eq_u32_e64 s[86:87], v76, v30
	v_cmp_eq_u32_e64 s[88:89], v80, v32
	v_cmp_eq_u32_e64 s[90:91], v84, v33
	s_mov_b64 exec, s[84:85]
	v_pk_mov_b32 v[72:73], v[72:73], v[74:75] op_sel:[1,0] op_sel_hi:[1,0]
	v_pk_mov_b32 v[74:75], v[74:75], v[70:71] op_sel:[1,0] op_sel_hi:[1,0]
	s_mov_b64 exec, s[86:87]
	v_pk_mov_b32 v[76:77], v[76:77], v[78:79] op_sel:[1,0] op_sel_hi:[1,0]
	v_pk_mov_b32 v[78:79], v[78:79], v[70:71] op_sel:[1,0] op_sel_hi:[1,0]
	s_mov_b64 exec, s[88:89]
	v_pk_mov_b32 v[80:81], v[80:81], v[82:83] op_sel:[1,0] op_sel_hi:[1,0]
	v_pk_mov_b32 v[82:83], v[82:83], v[70:71] op_sel:[1,0] op_sel_hi:[1,0]
	s_mov_b64 exec, s[90:91]
	v_pk_mov_b32 v[84:85], v[84:85], v[86:87] op_sel:[1,0] op_sel_hi:[1,0]
	v_pk_mov_b32 v[86:87], v[86:87], v[70:71] op_sel:[1,0] op_sel_hi:[1,0]
	s_lshl_b64 exec, s[78:79], s40
	s_add_i32 s40, s40, 1
	v_pk_mov_b32 v[4:5], v[32:33], v[32:33] op_sel:[1,0] op_sel_hi:[1,0]
	v_pk_mov_b32 v[6:7], v[30:31], v[30:31] op_sel:[1,0] op_sel_hi:[1,0]
	s_mov_b64 exec, -1
	s_cmp_lg_u32 s40, 8
	s_cbranch_scc1 .LBB0_1375
	v_max_u32_dpp v31, v72, v72 row_ror:1 row_mask:0xf bank_mask:0xf bound_ctrl:1
	v_max_u32_dpp v30, v76, v76 row_ror:1 row_mask:0xf bank_mask:0xf bound_ctrl:1
	v_max_u32_dpp v32, v80, v80 row_ror:1 row_mask:0xf bank_mask:0xf bound_ctrl:1
	v_max_u32_dpp v31, v31, v31 row_ror:2 row_mask:0xf bank_mask:0xf bound_ctrl:1
	v_max_u32_dpp v33, v84, v84 row_ror:1 row_mask:0xf bank_mask:0xf bound_ctrl:1
	v_max_u32_dpp v30, v30, v30 row_ror:2 row_mask:0xf bank_mask:0xf bound_ctrl:1
	v_max_u32_dpp v32, v32, v32 row_ror:2 row_mask:0xf bank_mask:0xf bound_ctrl:1
	v_max_u32_dpp v31, v31, v31 row_ror:4 row_mask:0xf bank_mask:0xf bound_ctrl:1
	v_max_u32_dpp v33, v33, v33 row_ror:2 row_mask:0xf bank_mask:0xf bound_ctrl:1
	v_max_u32_dpp v30, v30, v30 row_ror:4 row_mask:0xf bank_mask:0xf bound_ctrl:1
	v_max_u32_dpp v32, v32, v32 row_ror:4 row_mask:0xf bank_mask:0xf bound_ctrl:1
	v_max_u32_dpp v31, v31, v31 row_ror:8 row_mask:0xf bank_mask:0xf bound_ctrl:1
	v_max_u32_dpp v33, v33, v33 row_ror:4 row_mask:0xf bank_mask:0xf bound_ctrl:1
	v_max_u32_dpp v30, v30, v30 row_ror:8 row_mask:0xf bank_mask:0xf bound_ctrl:1
	v_max_u32_dpp v32, v32, v32 row_ror:8 row_mask:0xf bank_mask:0xf bound_ctrl:1
	v_max_u32_dpp v33, v33, v33 row_ror:8 row_mask:0xf bank_mask:0xf bound_ctrl:1
	v_cmp_eq_u32_e64 s[84:85], v72, v31
	v_cmp_eq_u32_e64 s[86:87], v76, v30
	v_cmp_eq_u32_e64 s[88:89], v80, v32
	v_cmp_eq_u32_e64 s[90:91], v84, v33
	s_mov_b64 exec, s[84:85]
	v_pk_mov_b32 v[72:73], v[72:73], v[74:75] op_sel:[1,0] op_sel_hi:[1,0]
	v_pk_mov_b32 v[74:75], v[74:75], v[70:71] op_sel:[1,0] op_sel_hi:[1,0]
	s_mov_b64 exec, s[86:87]
	v_pk_mov_b32 v[76:77], v[76:77], v[78:79] op_sel:[1,0] op_sel_hi:[1,0]
	v_pk_mov_b32 v[78:79], v[78:79], v[70:71] op_sel:[1,0] op_sel_hi:[1,0]
	s_mov_b64 exec, s[88:89]
	v_pk_mov_b32 v[80:81], v[80:81], v[82:83] op_sel:[1,0] op_sel_hi:[1,0]
	v_pk_mov_b32 v[82:83], v[82:83], v[70:71] op_sel:[1,0] op_sel_hi:[1,0]
	s_mov_b64 exec, s[90:91]
	v_pk_mov_b32 v[84:85], v[84:85], v[86:87] op_sel:[1,0] op_sel_hi:[1,0]
	v_pk_mov_b32 v[86:87], v[86:87], v[70:71] op_sel:[1,0] op_sel_hi:[1,0]
	s_lshl_b64 exec, s[78:79], s40
	s_add_i32 s40, s40, 1
	v_pk_mov_b32 v[4:5], v[32:33], v[32:33] op_sel:[1,0] op_sel_hi:[1,0]
	v_pk_mov_b32 v[6:7], v[30:31], v[30:31] op_sel:[1,0] op_sel_hi:[1,0]
	s_mov_b64 exec, -1
	v_max_u32_dpp v31, v72, v72 row_ror:1 row_mask:0xf bank_mask:0xf bound_ctrl:1
	v_max_u32_dpp v30, v76, v76 row_ror:1 row_mask:0xf bank_mask:0xf bound_ctrl:1
	v_max_u32_dpp v32, v80, v80 row_ror:1 row_mask:0xf bank_mask:0xf bound_ctrl:1
	v_max_u32_dpp v31, v31, v31 row_ror:2 row_mask:0xf bank_mask:0xf bound_ctrl:1
	v_max_u32_dpp v33, v84, v84 row_ror:1 row_mask:0xf bank_mask:0xf bound_ctrl:1
	v_max_u32_dpp v30, v30, v30 row_ror:2 row_mask:0xf bank_mask:0xf bound_ctrl:1
	v_max_u32_dpp v32, v32, v32 row_ror:2 row_mask:0xf bank_mask:0xf bound_ctrl:1
	v_max_u32_dpp v31, v31, v31 row_ror:4 row_mask:0xf bank_mask:0xf bound_ctrl:1
	v_max_u32_dpp v33, v33, v33 row_ror:2 row_mask:0xf bank_mask:0xf bound_ctrl:1
	v_max_u32_dpp v30, v30, v30 row_ror:4 row_mask:0xf bank_mask:0xf bound_ctrl:1
	v_max_u32_dpp v32, v32, v32 row_ror:4 row_mask:0xf bank_mask:0xf bound_ctrl:1
	v_max_u32_dpp v31, v31, v31 row_ror:8 row_mask:0xf bank_mask:0xf bound_ctrl:1
	v_max_u32_dpp v33, v33, v33 row_ror:4 row_mask:0xf bank_mask:0xf bound_ctrl:1
	v_max_u32_dpp v30, v30, v30 row_ror:8 row_mask:0xf bank_mask:0xf bound_ctrl:1
	v_max_u32_dpp v32, v32, v32 row_ror:8 row_mask:0xf bank_mask:0xf bound_ctrl:1
	v_max_u32_dpp v33, v33, v33 row_ror:8 row_mask:0xf bank_mask:0xf bound_ctrl:1
	v_cmp_eq_u32_e64 s[84:85], v72, v31
	v_cmp_eq_u32_e64 s[86:87], v76, v30
	v_cmp_eq_u32_e64 s[88:89], v80, v32
	v_cmp_eq_u32_e64 s[90:91], v84, v33
	s_mov_b64 exec, s[84:85]
	v_pk_mov_b32 v[72:73], v[72:73], v[74:75] op_sel:[1,0] op_sel_hi:[1,0]
	v_pk_mov_b32 v[74:75], v[74:75], v[70:71] op_sel:[1,0] op_sel_hi:[1,0]
	s_mov_b64 exec, s[86:87]
	v_pk_mov_b32 v[76:77], v[76:77], v[78:79] op_sel:[1,0] op_sel_hi:[1,0]
	v_pk_mov_b32 v[78:79], v[78:79], v[70:71] op_sel:[1,0] op_sel_hi:[1,0]
	s_mov_b64 exec, s[88:89]
	v_pk_mov_b32 v[80:81], v[80:81], v[82:83] op_sel:[1,0] op_sel_hi:[1,0]
	v_pk_mov_b32 v[82:83], v[82:83], v[70:71] op_sel:[1,0] op_sel_hi:[1,0]
	s_mov_b64 exec, s[90:91]
	v_pk_mov_b32 v[84:85], v[84:85], v[86:87] op_sel:[1,0] op_sel_hi:[1,0]
	v_pk_mov_b32 v[86:87], v[86:87], v[70:71] op_sel:[1,0] op_sel_hi:[1,0]
	s_lshl_b64 exec, s[78:79], s40
	s_add_i32 s40, s40, 1
	v_pk_mov_b32 v[4:5], v[32:33], v[32:33] op_sel:[1,0] op_sel_hi:[1,0]
	v_pk_mov_b32 v[6:7], v[30:31], v[30:31] op_sel:[1,0] op_sel_hi:[1,0]
	s_mov_b64 exec, -1
	v_max_u32_dpp v31, v72, v72 row_ror:1 row_mask:0xf bank_mask:0xf bound_ctrl:1
	v_max_u32_dpp v30, v76, v76 row_ror:1 row_mask:0xf bank_mask:0xf bound_ctrl:1
	v_max_u32_dpp v32, v80, v80 row_ror:1 row_mask:0xf bank_mask:0xf bound_ctrl:1
	v_max_u32_dpp v31, v31, v31 row_ror:2 row_mask:0xf bank_mask:0xf bound_ctrl:1
	v_max_u32_dpp v33, v84, v84 row_ror:1 row_mask:0xf bank_mask:0xf bound_ctrl:1
	v_max_u32_dpp v30, v30, v30 row_ror:2 row_mask:0xf bank_mask:0xf bound_ctrl:1
	v_max_u32_dpp v32, v32, v32 row_ror:2 row_mask:0xf bank_mask:0xf bound_ctrl:1
	v_max_u32_dpp v31, v31, v31 row_ror:4 row_mask:0xf bank_mask:0xf bound_ctrl:1
	v_max_u32_dpp v33, v33, v33 row_ror:2 row_mask:0xf bank_mask:0xf bound_ctrl:1
	v_max_u32_dpp v30, v30, v30 row_ror:4 row_mask:0xf bank_mask:0xf bound_ctrl:1
	v_max_u32_dpp v32, v32, v32 row_ror:4 row_mask:0xf bank_mask:0xf bound_ctrl:1
	v_max_u32_dpp v31, v31, v31 row_ror:8 row_mask:0xf bank_mask:0xf bound_ctrl:1
	v_max_u32_dpp v33, v33, v33 row_ror:4 row_mask:0xf bank_mask:0xf bound_ctrl:1
	v_max_u32_dpp v30, v30, v30 row_ror:8 row_mask:0xf bank_mask:0xf bound_ctrl:1
	v_max_u32_dpp v32, v32, v32 row_ror:8 row_mask:0xf bank_mask:0xf bound_ctrl:1
	v_max_u32_dpp v33, v33, v33 row_ror:8 row_mask:0xf bank_mask:0xf bound_ctrl:1
	v_cmp_eq_u32_e64 s[84:85], v72, v31
	v_cmp_eq_u32_e64 s[86:87], v76, v30
	v_cmp_eq_u32_e64 s[88:89], v80, v32
	v_cmp_eq_u32_e64 s[90:91], v84, v33
	s_mov_b64 exec, s[84:85]
	v_pk_mov_b32 v[72:73], v[72:73], v[74:75] op_sel:[1,0] op_sel_hi:[1,0]
	v_pk_mov_b32 v[74:75], v[74:75], v[70:71] op_sel:[1,0] op_sel_hi:[1,0]
	s_mov_b64 exec, s[86:87]
	v_pk_mov_b32 v[76:77], v[76:77], v[78:79] op_sel:[1,0] op_sel_hi:[1,0]
	v_pk_mov_b32 v[78:79], v[78:79], v[70:71] op_sel:[1,0] op_sel_hi:[1,0]
	s_mov_b64 exec, s[88:89]
	v_pk_mov_b32 v[80:81], v[80:81], v[82:83] op_sel:[1,0] op_sel_hi:[1,0]
	v_pk_mov_b32 v[82:83], v[82:83], v[70:71] op_sel:[1,0] op_sel_hi:[1,0]
	s_mov_b64 exec, s[90:91]
	v_pk_mov_b32 v[84:85], v[84:85], v[86:87] op_sel:[1,0] op_sel_hi:[1,0]
	v_pk_mov_b32 v[86:87], v[86:87], v[70:71] op_sel:[1,0] op_sel_hi:[1,0]
	s_lshl_b64 exec, s[78:79], s40
	s_add_i32 s40, s40, 1
	v_pk_mov_b32 v[4:5], v[32:33], v[32:33] op_sel:[1,0] op_sel_hi:[1,0]
	v_pk_mov_b32 v[6:7], v[30:31], v[30:31] op_sel:[1,0] op_sel_hi:[1,0]
	s_mov_b64 exec, -1
	v_max_u32_dpp v31, v72, v72 row_ror:1 row_mask:0xf bank_mask:0xf bound_ctrl:1
	v_max_u32_dpp v30, v76, v76 row_ror:1 row_mask:0xf bank_mask:0xf bound_ctrl:1
	v_max_u32_dpp v32, v80, v80 row_ror:1 row_mask:0xf bank_mask:0xf bound_ctrl:1
	v_max_u32_dpp v31, v31, v31 row_ror:2 row_mask:0xf bank_mask:0xf bound_ctrl:1
	v_max_u32_dpp v33, v84, v84 row_ror:1 row_mask:0xf bank_mask:0xf bound_ctrl:1
	v_max_u32_dpp v30, v30, v30 row_ror:2 row_mask:0xf bank_mask:0xf bound_ctrl:1
	v_max_u32_dpp v32, v32, v32 row_ror:2 row_mask:0xf bank_mask:0xf bound_ctrl:1
	v_max_u32_dpp v31, v31, v31 row_ror:4 row_mask:0xf bank_mask:0xf bound_ctrl:1
	v_max_u32_dpp v33, v33, v33 row_ror:2 row_mask:0xf bank_mask:0xf bound_ctrl:1
	v_max_u32_dpp v30, v30, v30 row_ror:4 row_mask:0xf bank_mask:0xf bound_ctrl:1
	v_max_u32_dpp v32, v32, v32 row_ror:4 row_mask:0xf bank_mask:0xf bound_ctrl:1
	v_max_u32_dpp v31, v31, v31 row_ror:8 row_mask:0xf bank_mask:0xf bound_ctrl:1
	v_max_u32_dpp v33, v33, v33 row_ror:4 row_mask:0xf bank_mask:0xf bound_ctrl:1
	v_max_u32_dpp v30, v30, v30 row_ror:8 row_mask:0xf bank_mask:0xf bound_ctrl:1
	v_max_u32_dpp v32, v32, v32 row_ror:8 row_mask:0xf bank_mask:0xf bound_ctrl:1
	v_max_u32_dpp v33, v33, v33 row_ror:8 row_mask:0xf bank_mask:0xf bound_ctrl:1
	v_cmp_eq_u32_e64 s[84:85], v72, v31
	v_cmp_eq_u32_e64 s[86:87], v76, v30
	v_cmp_eq_u32_e64 s[88:89], v80, v32
	v_cmp_eq_u32_e64 s[90:91], v84, v33
	s_mov_b64 exec, s[84:85]
	v_pk_mov_b32 v[72:73], v[72:73], v[74:75] op_sel:[1,0] op_sel_hi:[1,0]
	v_pk_mov_b32 v[74:75], v[74:75], v[70:71] op_sel:[1,0] op_sel_hi:[1,0]
	s_mov_b64 exec, s[86:87]
	v_pk_mov_b32 v[76:77], v[76:77], v[78:79] op_sel:[1,0] op_sel_hi:[1,0]
	v_pk_mov_b32 v[78:79], v[78:79], v[70:71] op_sel:[1,0] op_sel_hi:[1,0]
	s_mov_b64 exec, s[88:89]
	v_pk_mov_b32 v[80:81], v[80:81], v[82:83] op_sel:[1,0] op_sel_hi:[1,0]
	v_pk_mov_b32 v[82:83], v[82:83], v[70:71] op_sel:[1,0] op_sel_hi:[1,0]
	s_mov_b64 exec, s[90:91]
	v_pk_mov_b32 v[84:85], v[84:85], v[86:87] op_sel:[1,0] op_sel_hi:[1,0]
	v_pk_mov_b32 v[86:87], v[86:87], v[70:71] op_sel:[1,0] op_sel_hi:[1,0]
	s_lshl_b64 exec, s[78:79], s40
	s_add_i32 s40, s40, 1
	v_pk_mov_b32 v[4:5], v[32:33], v[32:33] op_sel:[1,0] op_sel_hi:[1,0]
	v_pk_mov_b32 v[6:7], v[30:31], v[30:31] op_sel:[1,0] op_sel_hi:[1,0]
	s_mov_b64 exec, -1
	v_max_u32_dpp v31, v72, v72 row_ror:1 row_mask:0xf bank_mask:0xf bound_ctrl:1
	v_max_u32_dpp v30, v76, v76 row_ror:1 row_mask:0xf bank_mask:0xf bound_ctrl:1
	v_max_u32_dpp v32, v80, v80 row_ror:1 row_mask:0xf bank_mask:0xf bound_ctrl:1
	v_max_u32_dpp v31, v31, v31 row_ror:2 row_mask:0xf bank_mask:0xf bound_ctrl:1
	v_max_u32_dpp v33, v84, v84 row_ror:1 row_mask:0xf bank_mask:0xf bound_ctrl:1
	v_max_u32_dpp v30, v30, v30 row_ror:2 row_mask:0xf bank_mask:0xf bound_ctrl:1
	v_max_u32_dpp v32, v32, v32 row_ror:2 row_mask:0xf bank_mask:0xf bound_ctrl:1
	v_max_u32_dpp v31, v31, v31 row_ror:4 row_mask:0xf bank_mask:0xf bound_ctrl:1
	v_max_u32_dpp v33, v33, v33 row_ror:2 row_mask:0xf bank_mask:0xf bound_ctrl:1
	v_max_u32_dpp v30, v30, v30 row_ror:4 row_mask:0xf bank_mask:0xf bound_ctrl:1
	v_max_u32_dpp v32, v32, v32 row_ror:4 row_mask:0xf bank_mask:0xf bound_ctrl:1
	v_max_u32_dpp v31, v31, v31 row_ror:8 row_mask:0xf bank_mask:0xf bound_ctrl:1
	v_max_u32_dpp v33, v33, v33 row_ror:4 row_mask:0xf bank_mask:0xf bound_ctrl:1
	v_max_u32_dpp v30, v30, v30 row_ror:8 row_mask:0xf bank_mask:0xf bound_ctrl:1
	v_max_u32_dpp v32, v32, v32 row_ror:8 row_mask:0xf bank_mask:0xf bound_ctrl:1
	v_max_u32_dpp v33, v33, v33 row_ror:8 row_mask:0xf bank_mask:0xf bound_ctrl:1
	v_cmp_eq_u32_e64 s[84:85], v72, v31
	v_cmp_eq_u32_e64 s[86:87], v76, v30
	v_cmp_eq_u32_e64 s[88:89], v80, v32
	v_cmp_eq_u32_e64 s[90:91], v84, v33
	s_mov_b64 exec, s[84:85]
	v_pk_mov_b32 v[72:73], v[72:73], v[74:75] op_sel:[1,0] op_sel_hi:[1,0]
	v_pk_mov_b32 v[74:75], v[74:75], v[70:71] op_sel:[1,0] op_sel_hi:[1,0]
	s_mov_b64 exec, s[86:87]
	v_pk_mov_b32 v[76:77], v[76:77], v[78:79] op_sel:[1,0] op_sel_hi:[1,0]
	v_pk_mov_b32 v[78:79], v[78:79], v[70:71] op_sel:[1,0] op_sel_hi:[1,0]
	s_mov_b64 exec, s[88:89]
	v_pk_mov_b32 v[80:81], v[80:81], v[82:83] op_sel:[1,0] op_sel_hi:[1,0]
	v_pk_mov_b32 v[82:83], v[82:83], v[70:71] op_sel:[1,0] op_sel_hi:[1,0]
	s_mov_b64 exec, s[90:91]
	v_pk_mov_b32 v[84:85], v[84:85], v[86:87] op_sel:[1,0] op_sel_hi:[1,0]
	v_pk_mov_b32 v[86:87], v[86:87], v[70:71] op_sel:[1,0] op_sel_hi:[1,0]
	s_lshl_b64 exec, s[78:79], s40
	s_add_i32 s40, s40, 1
	v_pk_mov_b32 v[4:5], v[32:33], v[32:33] op_sel:[1,0] op_sel_hi:[1,0]
	v_pk_mov_b32 v[6:7], v[30:31], v[30:31] op_sel:[1,0] op_sel_hi:[1,0]
	s_mov_b64 exec, -1
	v_max_u32_dpp v31, v72, v72 row_ror:1 row_mask:0xf bank_mask:0xf bound_ctrl:1
	v_max_u32_dpp v30, v76, v76 row_ror:1 row_mask:0xf bank_mask:0xf bound_ctrl:1
	v_max_u32_dpp v32, v80, v80 row_ror:1 row_mask:0xf bank_mask:0xf bound_ctrl:1
	v_max_u32_dpp v31, v31, v31 row_ror:2 row_mask:0xf bank_mask:0xf bound_ctrl:1
	v_max_u32_dpp v33, v84, v84 row_ror:1 row_mask:0xf bank_mask:0xf bound_ctrl:1
	v_max_u32_dpp v30, v30, v30 row_ror:2 row_mask:0xf bank_mask:0xf bound_ctrl:1
	v_max_u32_dpp v32, v32, v32 row_ror:2 row_mask:0xf bank_mask:0xf bound_ctrl:1
	v_max_u32_dpp v31, v31, v31 row_ror:4 row_mask:0xf bank_mask:0xf bound_ctrl:1
	v_max_u32_dpp v33, v33, v33 row_ror:2 row_mask:0xf bank_mask:0xf bound_ctrl:1
	v_max_u32_dpp v30, v30, v30 row_ror:4 row_mask:0xf bank_mask:0xf bound_ctrl:1
	v_max_u32_dpp v32, v32, v32 row_ror:4 row_mask:0xf bank_mask:0xf bound_ctrl:1
	v_max_u32_dpp v31, v31, v31 row_ror:8 row_mask:0xf bank_mask:0xf bound_ctrl:1
	v_max_u32_dpp v33, v33, v33 row_ror:4 row_mask:0xf bank_mask:0xf bound_ctrl:1
	v_max_u32_dpp v30, v30, v30 row_ror:8 row_mask:0xf bank_mask:0xf bound_ctrl:1
	v_max_u32_dpp v32, v32, v32 row_ror:8 row_mask:0xf bank_mask:0xf bound_ctrl:1
	v_max_u32_dpp v33, v33, v33 row_ror:8 row_mask:0xf bank_mask:0xf bound_ctrl:1
	v_cmp_eq_u32_e64 s[84:85], v72, v31
	v_cmp_eq_u32_e64 s[86:87], v76, v30
	v_cmp_eq_u32_e64 s[88:89], v80, v32
	v_cmp_eq_u32_e64 s[90:91], v84, v33
	s_mov_b64 exec, s[84:85]
	v_pk_mov_b32 v[72:73], v[72:73], v[74:75] op_sel:[1,0] op_sel_hi:[1,0]
	s_mov_b64 exec, s[86:87]
	v_pk_mov_b32 v[76:77], v[76:77], v[78:79] op_sel:[1,0] op_sel_hi:[1,0]
	s_mov_b64 exec, s[88:89]
	v_pk_mov_b32 v[80:81], v[80:81], v[82:83] op_sel:[1,0] op_sel_hi:[1,0]
	s_mov_b64 exec, s[90:91]
	v_pk_mov_b32 v[84:85], v[84:85], v[86:87] op_sel:[1,0] op_sel_hi:[1,0]
	s_lshl_b64 exec, s[78:79], s40
	s_add_i32 s40, s40, 1
	v_pk_mov_b32 v[4:5], v[32:33], v[32:33] op_sel:[1,0] op_sel_hi:[1,0]
	v_pk_mov_b32 v[6:7], v[30:31], v[30:31] op_sel:[1,0] op_sel_hi:[1,0]
	s_mov_b64 exec, -1
	v_max_u32_dpp v31, v72, v72 row_ror:1 row_mask:0xf bank_mask:0xf bound_ctrl:1
	v_max_u32_dpp v30, v76, v76 row_ror:1 row_mask:0xf bank_mask:0xf bound_ctrl:1
	v_max_u32_dpp v32, v80, v80 row_ror:1 row_mask:0xf bank_mask:0xf bound_ctrl:1
	v_max_u32_dpp v31, v31, v31 row_ror:2 row_mask:0xf bank_mask:0xf bound_ctrl:1
	v_max_u32_dpp v33, v84, v84 row_ror:1 row_mask:0xf bank_mask:0xf bound_ctrl:1
	v_max_u32_dpp v30, v30, v30 row_ror:2 row_mask:0xf bank_mask:0xf bound_ctrl:1
	v_max_u32_dpp v32, v32, v32 row_ror:2 row_mask:0xf bank_mask:0xf bound_ctrl:1
	v_max_u32_dpp v31, v31, v31 row_ror:4 row_mask:0xf bank_mask:0xf bound_ctrl:1
	v_max_u32_dpp v33, v33, v33 row_ror:2 row_mask:0xf bank_mask:0xf bound_ctrl:1
	v_max_u32_dpp v30, v30, v30 row_ror:4 row_mask:0xf bank_mask:0xf bound_ctrl:1
	v_max_u32_dpp v32, v32, v32 row_ror:4 row_mask:0xf bank_mask:0xf bound_ctrl:1
	v_max_u32_dpp v31, v31, v31 row_ror:8 row_mask:0xf bank_mask:0xf bound_ctrl:1
	v_max_u32_dpp v33, v33, v33 row_ror:4 row_mask:0xf bank_mask:0xf bound_ctrl:1
	v_max_u32_dpp v30, v30, v30 row_ror:8 row_mask:0xf bank_mask:0xf bound_ctrl:1
	v_max_u32_dpp v32, v32, v32 row_ror:8 row_mask:0xf bank_mask:0xf bound_ctrl:1
	v_max_u32_dpp v33, v33, v33 row_ror:8 row_mask:0xf bank_mask:0xf bound_ctrl:1
	v_cmp_eq_u32_e64 s[84:85], v72, v31
	v_cmp_eq_u32_e64 s[86:87], v76, v30
	v_cmp_eq_u32_e64 s[88:89], v80, v32
	v_cmp_eq_u32_e64 s[90:91], v84, v33
	s_mov_b64 exec, s[84:85]
	v_pk_mov_b32 v[72:73], v[72:73], v[74:75] op_sel:[1,0] op_sel_hi:[1,0]
	s_mov_b64 exec, s[86:87]
	v_pk_mov_b32 v[76:77], v[76:77], v[78:79] op_sel:[1,0] op_sel_hi:[1,0]
	s_mov_b64 exec, s[88:89]
	v_pk_mov_b32 v[80:81], v[80:81], v[82:83] op_sel:[1,0] op_sel_hi:[1,0]
	s_mov_b64 exec, s[90:91]
	v_pk_mov_b32 v[84:85], v[84:85], v[86:87] op_sel:[1,0] op_sel_hi:[1,0]
	s_lshl_b64 exec, s[78:79], s40
	s_add_i32 s40, s40, 1
	v_pk_mov_b32 v[4:5], v[32:33], v[32:33] op_sel:[1,0] op_sel_hi:[1,0]
	v_pk_mov_b32 v[6:7], v[30:31], v[30:31] op_sel:[1,0] op_sel_hi:[1,0]
	s_mov_b64 exec, -1
	v_max_u32_dpp v31, v72, v72 row_ror:1 row_mask:0xf bank_mask:0xf bound_ctrl:1
	v_max_u32_dpp v30, v76, v76 row_ror:1 row_mask:0xf bank_mask:0xf bound_ctrl:1
	v_max_u32_dpp v32, v80, v80 row_ror:1 row_mask:0xf bank_mask:0xf bound_ctrl:1
	v_max_u32_dpp v31, v31, v31 row_ror:2 row_mask:0xf bank_mask:0xf bound_ctrl:1
	v_max_u32_dpp v33, v84, v84 row_ror:1 row_mask:0xf bank_mask:0xf bound_ctrl:1
	v_max_u32_dpp v30, v30, v30 row_ror:2 row_mask:0xf bank_mask:0xf bound_ctrl:1
	v_max_u32_dpp v32, v32, v32 row_ror:2 row_mask:0xf bank_mask:0xf bound_ctrl:1
	v_max_u32_dpp v31, v31, v31 row_ror:4 row_mask:0xf bank_mask:0xf bound_ctrl:1
	v_max_u32_dpp v33, v33, v33 row_ror:2 row_mask:0xf bank_mask:0xf bound_ctrl:1
	v_max_u32_dpp v30, v30, v30 row_ror:4 row_mask:0xf bank_mask:0xf bound_ctrl:1
	v_max_u32_dpp v32, v32, v32 row_ror:4 row_mask:0xf bank_mask:0xf bound_ctrl:1
	v_max_u32_dpp v31, v31, v31 row_ror:8 row_mask:0xf bank_mask:0xf bound_ctrl:1
	v_max_u32_dpp v33, v33, v33 row_ror:4 row_mask:0xf bank_mask:0xf bound_ctrl:1
	v_max_u32_dpp v30, v30, v30 row_ror:8 row_mask:0xf bank_mask:0xf bound_ctrl:1
	v_max_u32_dpp v32, v32, v32 row_ror:8 row_mask:0xf bank_mask:0xf bound_ctrl:1
	v_max_u32_dpp v33, v33, v33 row_ror:8 row_mask:0xf bank_mask:0xf bound_ctrl:1
	s_lshl_b64 exec, s[78:79], s40
	v_pk_mov_b32 v[4:5], v[32:33], v[32:33] op_sel:[1,0] op_sel_hi:[1,0]
	v_pk_mov_b32 v[6:7], v[30:31], v[30:31] op_sel:[1,0] op_sel_hi:[1,0]
	s_mov_b64 exec, -1
	v_max_u32_dpp v15, v7, v7 row_ror:1 row_mask:0xf bank_mask:0xf bound_ctrl:1
	v_cmp_lt_i32_e32 vcc, -1, v7
	v_bitop3_b32 v11, v18, s60, v18 bitop3:0xc
	v_max_u32_dpp v15, v15, v15 row_ror:2 row_mask:0xf bank_mask:0xf bound_ctrl:1
	v_cndmask_b32_e64 v14, v217, -1, vcc
	v_bitop3_b32 v14, v14, v7, s59 bitop3:0x78
	v_max_u32_dpp v15, v15, v15 row_ror:4 row_mask:0xf bank_mask:0xf bound_ctrl:1
	v_not_b32_e32 v13, v7
	v_lshrrev_b32_e32 v13, 4, v13
	v_max_u32_dpp v15, v15, v15 row_ror:8 row_mask:0xf bank_mask:0xf bound_ctrl:1
	v_cmp_lt_i32_e32 vcc, -1, v15
	v_and_or_b32 v13, v13, 15, v195
	v_lshlrev_b32_e32 v13, 2, v13
	v_cndmask_b32_e64 v18, v217, -1, vcc
	v_bitop3_b32 v15, v18, v15, s59 bitop3:0x78
	v_sub_f32_e32 v14, v14, v15
	v_mul_f32_e32 v14, 0x3fb8aa3b, v14
	v_exp_f32_e32 v14, v14
	ds_bpermute_b32 v11, v13, v11
	v_bitop3_b32 v7, v7, v195, 15 bitop3:0xce
	v_bitop3_b32 v0, v0, s60, v0 bitop3:0xc
	v_add_f32_dpp v13, v14, v14 row_ror:1 row_mask:0xf bank_mask:0xf bound_ctrl:1
	v_lshlrev_b32_e32 v7, 2, v7
	ds_bpermute_b32 v0, v7, v0
	v_add_f32_dpp v13, v13, v13 row_ror:2 row_mask:0xf bank_mask:0xf bound_ctrl:1
	v_bitop3_b32 v10, v19, s60, v19 bitop3:0xc
	v_bitop3_b32 v9, v20, s60, v20 bitop3:0xc
	v_add_f32_dpp v13, v13, v13 row_ror:4 row_mask:0xf bank_mask:0xf bound_ctrl:1
	v_lshl_or_b32 v12, s33, 4, v171
	s_waitcnt lgkmcnt(0)
	v_lshl_add_u32 v0, v11, 7, v0
	v_add_f32_dpp v13, v13, v13 row_ror:8 row_mask:0xf bank_mask:0xf bound_ctrl:1
	v_div_scale_f32 v15, s[0:1], v13, v13, v14
	v_rcp_f32_e32 v18, v15
	v_bitop3_b32 v1, v1, s60, v1 bitop3:0xc
	v_bitop3_b32 v2, v2, s60, v2 bitop3:0xc
	v_bitop3_b32 v3, v3, s60, v3 bitop3:0xc
	v_fma_f32 v7, -v15, v18, 1.0
	v_fmac_f32_e32 v18, v7, v18
	v_div_scale_f32 v7, vcc, v14, v13, v14
	v_mul_f32_e32 v19, v7, v18
	v_fma_f32 v20, -v15, v19, v7
	v_fmac_f32_e32 v19, v20, v18
	v_fma_f32 v7, -v15, v19, v7
	v_div_fmas_f32 v7, v7, v18, v19
	v_div_fixup_f32 v7, v7, v13, v14
	v_or_b32_e32 v13, v12, v183
	v_lshl_add_u32 v11, v13, 1, s63
	v_cvt_f16_f32_e32 v7, v7
	v_max_u32_dpp v13, v6, v6 row_ror:1 row_mask:0xf bank_mask:0xf bound_ctrl:1
	v_cmp_lt_i32_e32 vcc, -1, v6
	ds_write_b16 v11, v0
	ds_write_b16 v11, v7 offset:32768
	v_max_u32_dpp v13, v13, v13 row_ror:2 row_mask:0xf bank_mask:0xf bound_ctrl:1
	v_cndmask_b32_e64 v7, v217, -1, vcc
	v_bitop3_b32 v7, v7, v6, s59 bitop3:0x78
	v_max_u32_dpp v13, v13, v13 row_ror:4 row_mask:0xf bank_mask:0xf bound_ctrl:1
	v_not_b32_e32 v0, v6
	v_lshrrev_b32_e32 v0, 4, v0
	v_max_u32_dpp v13, v13, v13 row_ror:8 row_mask:0xf bank_mask:0xf bound_ctrl:1
	v_cmp_lt_i32_e32 vcc, -1, v13
	v_and_or_b32 v0, v0, 15, v195
	v_lshlrev_b32_e32 v0, 2, v0
	v_cndmask_b32_e64 v14, v217, -1, vcc
	v_bitop3_b32 v13, v14, v13, s59 bitop3:0x78
	v_sub_f32_e32 v7, v7, v13
	v_mul_f32_e32 v7, 0x3fb8aa3b, v7
	v_exp_f32_e32 v7, v7
	ds_bpermute_b32 v0, v0, v10
	v_bitop3_b32 v6, v6, v195, 15 bitop3:0xce
	v_lshlrev_b32_e32 v6, 2, v6
	v_add_f32_dpp v10, v7, v7 row_ror:1 row_mask:0xf bank_mask:0xf bound_ctrl:1
	ds_bpermute_b32 v1, v6, v1
	v_bitop3_b32 v8, v21, s60, v21 bitop3:0xc
	v_add_f32_dpp v10, v10, v10 row_ror:2 row_mask:0xf bank_mask:0xf bound_ctrl:1
	s_waitcnt lgkmcnt(0)
	v_lshl_add_u32 v0, v0, 7, v1
	v_add_f32_dpp v10, v10, v10 row_ror:4 row_mask:0xf bank_mask:0xf bound_ctrl:1
	ds_write_b16 v11, v0 offset:256
	v_not_b32_e32 v1, v5
	v_add_f32_dpp v10, v10, v10 row_ror:8 row_mask:0xf bank_mask:0xf bound_ctrl:1
	v_div_scale_f32 v13, s[0:1], v10, v10, v7
	v_rcp_f32_e32 v14, v13
	v_lshrrev_b32_e32 v1, 4, v1
	v_and_or_b32 v1, v1, 15, v195
	v_lshlrev_b32_e32 v1, 2, v1
	v_fma_f32 v6, -v13, v14, 1.0
	v_fmac_f32_e32 v14, v6, v14
	v_div_scale_f32 v6, vcc, v7, v10, v7
	v_mul_f32_e32 v15, v6, v14
	v_fma_f32 v18, -v13, v15, v6
	v_fmac_f32_e32 v15, v18, v14
	v_fma_f32 v6, -v13, v15, v6
	v_div_fmas_f32 v6, v6, v14, v15
	v_div_fixup_f32 v6, v6, v10, v7
	v_max_u32_dpp v7, v5, v5 row_ror:1 row_mask:0xf bank_mask:0xf bound_ctrl:1
	v_cmp_lt_i32_e32 vcc, -1, v5
	v_cvt_f16_f32_e32 v0, v6
	v_max_u32_dpp v7, v7, v7 row_ror:2 row_mask:0xf bank_mask:0xf bound_ctrl:1
	v_cndmask_b32_e64 v6, v217, -1, vcc
	v_bitop3_b32 v6, v6, v5, s59 bitop3:0x78
	v_max_u32_dpp v7, v7, v7 row_ror:4 row_mask:0xf bank_mask:0xf bound_ctrl:1
	ds_bpermute_b32 v1, v1, v9
	v_bitop3_b32 v5, v5, v195, 15 bitop3:0xce
	v_max_u32_dpp v7, v7, v7 row_ror:8 row_mask:0xf bank_mask:0xf bound_ctrl:1
	v_cmp_lt_i32_e32 vcc, -1, v7
	v_lshlrev_b32_e32 v5, 2, v5
	ds_bpermute_b32 v2, v5, v2
	v_cndmask_b32_e64 v10, v217, -1, vcc
	v_bitop3_b32 v7, v10, v7, s59 bitop3:0x78
	v_sub_f32_e32 v6, v6, v7
	v_mul_f32_e32 v6, 0x3fb8aa3b, v6
	v_exp_f32_e32 v6, v6
	ds_write_b16 v11, v0 offset:33024
	s_waitcnt lgkmcnt(1)
	v_lshl_add_u32 v0, v1, 7, v2
	v_max_u32_dpp v2, v4, v4 row_ror:1 row_mask:0xf bank_mask:0xf bound_ctrl:1
	v_add_f32_dpp v7, v6, v6 row_ror:1 row_mask:0xf bank_mask:0xf bound_ctrl:1
	s_nop 0
	v_max_u32_dpp v2, v2, v2 row_ror:2 row_mask:0xf bank_mask:0xf bound_ctrl:1
	v_add_f32_dpp v7, v7, v7 row_ror:2 row_mask:0xf bank_mask:0xf bound_ctrl:1
	s_nop 0
	v_max_u32_dpp v2, v2, v2 row_ror:4 row_mask:0xf bank_mask:0xf bound_ctrl:1
	v_add_f32_dpp v7, v7, v7 row_ror:4 row_mask:0xf bank_mask:0xf bound_ctrl:1
	s_nop 0
	v_max_u32_dpp v2, v2, v2 row_ror:8 row_mask:0xf bank_mask:0xf bound_ctrl:1
	v_add_f32_dpp v7, v7, v7 row_ror:8 row_mask:0xf bank_mask:0xf bound_ctrl:1
	v_div_scale_f32 v9, s[0:1], v7, v7, v6
	v_rcp_f32_e32 v10, v9
	s_nop 0
	v_fma_f32 v5, -v9, v10, 1.0
	v_fmac_f32_e32 v10, v5, v10
	v_div_scale_f32 v5, vcc, v6, v7, v6
	v_mul_f32_e32 v13, v5, v10
	v_fma_f32 v14, -v9, v13, v5
	v_fmac_f32_e32 v13, v14, v10
	v_fma_f32 v5, -v9, v13, v5
	v_div_fmas_f32 v5, v5, v10, v13
	v_div_fixup_f32 v5, v5, v7, v6
	v_cvt_f16_f32_e32 v5, v5
	v_cmp_lt_i32_e32 vcc, -1, v4
	ds_write_b16 v11, v0 offset:512
	ds_write_b16 v11, v5 offset:33280
	v_cndmask_b32_e64 v1, v217, -1, vcc
	v_cmp_lt_i32_e32 vcc, -1, v2
	v_bitop3_b32 v1, v1, v4, s59 bitop3:0x78
	v_not_b32_e32 v0, v4
	v_cndmask_b32_e64 v5, v217, -1, vcc
	v_bitop3_b32 v2, v5, v2, s59 bitop3:0x78
	v_sub_f32_e32 v1, v1, v2
	v_mul_f32_e32 v1, 0x3fb8aa3b, v1
	v_exp_f32_e32 v1, v1
	v_bitop3_b32 v4, v4, v195, 15 bitop3:0xce
	v_lshlrev_b32_e32 v4, 2, v4
	v_lshrrev_b32_e32 v0, 4, v0
	v_add_f32_dpp v2, v1, v1 row_ror:1 row_mask:0xf bank_mask:0xf bound_ctrl:1
	ds_bpermute_b32 v3, v4, v3
	v_and_or_b32 v0, v0, 15, v195
	v_add_f32_dpp v2, v2, v2 row_ror:2 row_mask:0xf bank_mask:0xf bound_ctrl:1
	v_lshlrev_b32_e32 v0, 2, v0
	ds_bpermute_b32 v0, v0, v8
	v_add_f32_dpp v2, v2, v2 row_ror:4 row_mask:0xf bank_mask:0xf bound_ctrl:1
	s_waitcnt lgkmcnt(0)
	v_lshl_add_u32 v0, v0, 7, v3
	v_add_f32_dpp v2, v2, v2 row_ror:8 row_mask:0xf bank_mask:0xf bound_ctrl:1
	v_div_scale_f32 v5, s[0:1], v2, v2, v1
	v_rcp_f32_e32 v6, v5
	s_add_i32 s0, s33, 1
	s_cmp_lg_u32 s33, 7
	s_cselect_b32 s1, s0, 7
	v_fma_f32 v4, -v5, v6, 1.0
	v_fmac_f32_e32 v6, v4, v6
	v_div_scale_f32 v4, vcc, v1, v2, v1
	v_mul_f32_e32 v7, v4, v6
	v_fma_f32 v8, -v5, v7, v4
	v_fmac_f32_e32 v7, v8, v6
	v_fma_f32 v4, -v5, v7, v4
	v_div_fmas_f32 v4, v4, v6, v7
	v_div_fixup_f32 v1, v4, v2, v1
	v_add_u32_e32 v2, v12, v182
	v_cvt_f16_f32_e32 v1, v1
	v_lshl_or_b32 v2, v2, 1, v218
	s_lshl_b32 s40, s1, 16
	v_add_u32_e32 v2, s63, v2
	s_cmp_lt_u32 s1, 4
	ds_write_b16 v2, v0
	ds_write_b16 v2, v1 offset:32768
	v_lshl_add_u64 v[0:1], v[154:155], 0, s[40:41]
	s_cselect_b32 s33, s3, s56
	s_cselect_b32 s40, s2, s55
	v_mov_b32_e32 v2, s40
	v_mov_b32_e32 v3, s33
	s_lshl_b32 s1, s1, 9
	v_lshl_add_u64 v[2:3], v[16:17], 1, v[2:3]
	s_and_b32 s40, s1, 0x600
	v_lshl_add_u64 v[2:3], v[2:3], 0, s[40:41]
	v_lshl_add_u64 v[12:13], v[2:3], 0, v[148:149]
	s_cmp_eq_u32 s0, 8
	s_mov_b32 s33, s0
	s_cbranch_scc0 .LBB0_1346
	s_waitcnt lgkmcnt(0)
	s_barrier
	ds_read_b128 v[0:3], v185
	ds_read_b128 v[40:43], v185 offset:16
	s_ashr_i32 s49, s48, 31
	s_lshl_b64 s[0:1], s[48:49], 10
	v_lshl_add_u64 v[144:145], v[152:153], 0, s[0:1]
	s_waitcnt lgkmcnt(1)
	v_lshlrev_b32_e32 v4, 7, v0
	v_mad_u32_u16 v0, v0, s81, v150 op_sel:[1,0,0,0]
	v_and_or_b32 v64, v4, s68, v150
	v_mad_u32_u16 v4, v1, s81, v150
	global_load_dwordx4 v[60:63], v0, s[26:27]
	global_load_dwordx4 v[56:59], v4, s[26:27]
	v_mad_u32_u16 v0, v1, s81, v150 op_sel:[1,0,0,0]
	v_mad_u32_u16 v1, v2, s81, v150
	global_load_dwordx4 v[52:55], v0, s[26:27]
	global_load_dwordx4 v[48:51], v1, s[26:27]
	v_mad_u32_u16 v0, v2, s81, v150 op_sel:[1,0,0,0]
	v_mad_u32_u16 v1, v3, s81, v150
	global_load_dwordx4 v[44:47], v0, s[26:27]
	global_load_dwordx4 v[36:39], v1, s[26:27]
	v_mad_u32_u16 v0, v3, s81, v150 op_sel:[1,0,0,0]
	s_waitcnt lgkmcnt(0)
	v_mad_u32_u16 v1, v40, s81, v150
	global_load_dwordx4 v[32:35], v0, s[26:27]
	global_load_dwordx4 v[28:31], v1, s[26:27]
	v_mad_u32_u16 v0, v40, s81, v150 op_sel:[1,0,0,0]
	v_mad_u32_u16 v1, v41, s81, v150
	global_load_dwordx4 v[24:27], v0, s[26:27]
	global_load_dwordx4 v[20:23], v1, s[26:27]
	v_mad_u32_u16 v0, v41, s81, v150 op_sel:[1,0,0,0]
	v_mad_u32_u16 v1, v42, s81, v150
	global_load_dwordx4 v[16:19], v0, s[26:27]
	global_load_dwordx4 v[12:15], v1, s[26:27]
	v_mad_u32_u16 v0, v42, s81, v150 op_sel:[1,0,0,0]
	v_mad_u32_u16 v1, v43, s81, v150
	global_load_dwordx4 v[8:11], v0, s[26:27]
	global_load_dwordx4 v[4:7], v1, s[26:27]
	v_mad_u32_u16 v0, v43, s81, v150 op_sel:[1,0,0,0]
	global_load_dwordx4 v[0:3], v0, s[26:27]
	s_nop 0
	global_load_dwordx4 v[64:67], v64, s[26:27]
	s_nop 0
	global_load_dwordx4 v[40:43], v[144:145], off
	ds_read_b128 v[140:143], v185 offset:256
	ds_read_b128 v[136:139], v185 offset:272
	s_mov_b32 s76, 0
	s_waitcnt vmcnt(0)
	s_branch .LBB0_1379

.LBB0_1379:
	s_lshr_b32 s52, s76, 4
	s_and_b32 s40, s76, 14
	s_or_b32 s40, s40, 1
	s_lshl_b32 s40, s40, 10
	v_lshl_add_u64 v[80:81], v[144:145], 0, s[40:41]
	s_lshl_b32 s40, s52, 7
	v_lshl_add_u64 v[80:81], v[80:81], 0, s[40:41]
	global_load_dwordx4 v[80:83], v[80:81], off
	s_lshl_b32 s33, s52, 21
	s_add_u32 s50, s26, s33
	s_waitcnt lgkmcnt(1)
	v_mad_u32_u16 v68, v140, s81, v150
	v_mad_u32_u16 v69, v140, s81, v150 op_sel:[1,0,0,0]
	s_addc_u32 s51, s27, 0
	global_load_dwordx4 v[132:135], v68, s[50:51]
	global_load_dwordx4 v[128:131], v69, s[50:51]
	v_mad_u32_u16 v68, v141, s81, v150
	v_mad_u32_u16 v69, v141, s81, v150 op_sel:[1,0,0,0]
	global_load_dwordx4 v[124:127], v68, s[50:51]
	global_load_dwordx4 v[120:123], v69, s[50:51]
	v_mad_u32_u16 v68, v142, s81, v150
	v_mad_u32_u16 v69, v142, s81, v150 op_sel:[1,0,0,0]
	global_load_dwordx4 v[116:119], v68, s[50:51]
	global_load_dwordx4 v[112:115], v69, s[50:51]
	v_mad_u32_u16 v68, v143, s81, v150
	v_mad_u32_u16 v69, v143, s81, v150 op_sel:[1,0,0,0]
	global_load_dwordx4 v[108:111], v68, s[50:51]
	global_load_dwordx4 v[104:107], v69, s[50:51]
	s_waitcnt lgkmcnt(0)
	v_mad_u32_u16 v68, v136, s81, v150
	v_mad_u32_u16 v69, v136, s81, v150 op_sel:[1,0,0,0]
	global_load_dwordx4 v[100:103], v68, s[50:51]
	global_load_dwordx4 v[96:99], v69, s[50:51]
	v_mad_u32_u16 v68, v137, s81, v150
	v_mad_u32_u16 v69, v137, s81, v150 op_sel:[1,0,0,0]
	global_load_dwordx4 v[92:95], v68, s[50:51]
	global_load_dwordx4 v[88:91], v69, s[50:51]
	v_mad_u32_u16 v68, v138, s81, v150
	v_mad_u32_u16 v69, v138, s81, v150 op_sel:[1,0,0,0]
	s_add_i32 s33, s76, 2
	s_cmpk_gt_u32 s76, 0x7d
	global_load_dwordx4 v[84:87], v68, s[50:51]
	global_load_dwordx4 v[76:79], v69, s[50:51]
	v_mad_u32_u16 v68, v139, s81, v150
	v_mad_u32_u16 v69, v139, s81, v150 op_sel:[1,0,0,0]
	s_cselect_b64 s[48:49], -1, 0
	s_cmpk_lt_u32 s76, 0x7e
	s_cselect_b32 s77, s33, 0x7f
	global_load_dwordx4 v[72:75], v68, s[50:51]
	s_nop 0
	global_load_dwordx4 v[68:71], v69, s[50:51]
	s_and_b32 s50, s76, 14
	s_or_b32 s45, s50, 1
	s_and_b32 s40, s77, 15
	v_lshl_add_u32 v136, s40, 8, v185
	ds_read_b128 v[140:143], v136
	ds_read_b128 v[136:139], v136 offset:16
	v_mov_b32_e32 v146, 0
	s_waitcnt vmcnt(32)
	v_dot4c_i32_i8_e32 v146, v40, v64
	v_mov_b32_e32 v64, 0
	s_waitcnt vmcnt(31)
	v_dot4c_i32_i8_e32 v64, v40, v60
	v_mov_b32_e32 v60, 0
	s_waitcnt vmcnt(30)
	v_dot4c_i32_i8_e32 v60, v40, v56
	v_mov_b32_e32 v56, 0
	s_waitcnt vmcnt(29)
	v_dot4c_i32_i8_e32 v56, v40, v52
	v_mov_b32_e32 v52, 0
	s_waitcnt vmcnt(28)
	v_dot4c_i32_i8_e32 v52, v40, v48
	v_mov_b32_e32 v48, 0
	s_waitcnt vmcnt(27)
	v_dot4c_i32_i8_e32 v48, v40, v44
	v_mov_b32_e32 v44, 0
	s_waitcnt vmcnt(26)
	v_dot4c_i32_i8_e32 v44, v40, v36
	v_mov_b32_e32 v36, 0
	s_waitcnt vmcnt(25)
	v_dot4c_i32_i8_e32 v36, v40, v32
	v_mov_b32_e32 v32, 0
	s_waitcnt vmcnt(24)
	v_dot4c_i32_i8_e32 v32, v40, v28
	v_mov_b32_e32 v28, 0
	s_waitcnt vmcnt(23)
	v_dot4c_i32_i8_e32 v28, v40, v24
	v_mov_b32_e32 v24, 0
	s_waitcnt vmcnt(22)
	v_dot4c_i32_i8_e32 v24, v40, v20
	v_mov_b32_e32 v20, 0
	s_waitcnt vmcnt(21)
	v_dot4c_i32_i8_e32 v20, v40, v16
	v_mov_b32_e32 v16, 0
	s_waitcnt vmcnt(20)
	v_dot4c_i32_i8_e32 v16, v40, v12
	v_mov_b32_e32 v12, 0
	v_dot4c_i32_i8_e32 v64, v41, v61
	s_waitcnt vmcnt(19)
	v_dot4c_i32_i8_e32 v12, v40, v8
	v_mov_b32_e32 v8, 0
	v_dot4c_i32_i8_e32 v146, v41, v65
	v_dot4c_i32_i8_e32 v64, v42, v62
	v_dot4c_i32_i8_e32 v32, v41, v29
	v_dot4c_i32_i8_e32 v28, v41, v25
	s_waitcnt vmcnt(18)
	v_dot4c_i32_i8_e32 v8, v40, v4
	v_mov_b32_e32 v4, 0
	v_dot4c_i32_i8_e32 v146, v42, v66
	v_dot4c_i32_i8_e32 v64, v43, v63
	v_dot4c_i32_i8_e32 v60, v41, v57
	v_dot4c_i32_i8_e32 v32, v42, v30
	v_dot4c_i32_i8_e32 v28, v42, v26
	v_dot4c_i32_i8_e32 v24, v41, v21
	v_dot4c_i32_i8_e32 v16, v41, v13
	v_dot4c_i32_i8_e32 v12, v41, v9
	s_waitcnt vmcnt(17)
	v_dot4c_i32_i8_e32 v4, v40, v0
	v_dot4c_i32_i8_e32 v146, v43, v67
	v_dot4c_i32_i8_e32 v60, v42, v58
	v_dot4c_i32_i8_e32 v56, v41, v53
	v_dot4c_i32_i8_e32 v32, v43, v31
	v_dot4c_i32_i8_e32 v28, v43, v27
	v_dot4c_i32_i8_e32 v24, v42, v22
	v_dot4c_i32_i8_e32 v20, v41, v17
	v_dot4c_i32_i8_e32 v16, v42, v14
	v_dot4c_i32_i8_e32 v12, v42, v10
	v_dot4c_i32_i8_e32 v4, v41, v1
	v_add_u32_dpp v1, v64, v64 quad_perm:[1,0,3,2] row_mask:0xf bank_mask:0xf bound_ctrl:1
	v_dot4c_i32_i8_e32 v60, v43, v59
	v_dot4c_i32_i8_e32 v56, v42, v54
	v_dot4c_i32_i8_e32 v52, v41, v49
	v_dot4c_i32_i8_e32 v24, v43, v23
	v_dot4c_i32_i8_e32 v20, v42, v18
	v_dot4c_i32_i8_e32 v16, v43, v15
	v_dot4c_i32_i8_e32 v12, v43, v11
	v_add_u32_dpp v0, v146, v146 quad_perm:[1,0,3,2] row_mask:0xf bank_mask:0xf bound_ctrl:1
	v_add_u32_dpp v10, v32, v32 quad_perm:[1,0,3,2] row_mask:0xf bank_mask:0xf bound_ctrl:1
	v_add_u32_dpp v11, v28, v28 quad_perm:[1,0,3,2] row_mask:0xf bank_mask:0xf bound_ctrl:1
	v_add_u32_dpp v1, v1, v1 quad_perm:[2,3,0,1] row_mask:0xf bank_mask:0xf bound_ctrl:1
	v_dot4c_i32_i8_e32 v56, v43, v55
	v_dot4c_i32_i8_e32 v52, v42, v50
	v_dot4c_i32_i8_e32 v48, v41, v45
	v_dot4c_i32_i8_e32 v20, v43, v19
	v_dot4c_i32_i8_e32 v4, v42, v2
	v_add_u32_dpp v2, v60, v60 quad_perm:[1,0,3,2] row_mask:0xf bank_mask:0xf bound_ctrl:1
	v_add_u32_dpp v13, v24, v24 quad_perm:[1,0,3,2] row_mask:0xf bank_mask:0xf bound_ctrl:1
	v_add_u32_dpp v15, v16, v16 quad_perm:[1,0,3,2] row_mask:0xf bank_mask:0xf bound_ctrl:1
	v_add_u32_dpp v0, v0, v0 quad_perm:[2,3,0,1] row_mask:0xf bank_mask:0xf bound_ctrl:1
	v_add_u32_dpp v10, v10, v10 quad_perm:[2,3,0,1] row_mask:0xf bank_mask:0xf bound_ctrl:1
	v_add_u32_dpp v11, v11, v11 quad_perm:[2,3,0,1] row_mask:0xf bank_mask:0xf bound_ctrl:1
	v_mov_b32_dpp v16, v1 row_half_mirror row_mask:0xf bank_mask:0xf bound_ctrl:1
	v_dot4c_i32_i8_e32 v52, v43, v51
	v_dot4c_i32_i8_e32 v48, v42, v46
	v_dot4c_i32_i8_e32 v44, v41, v37
	v_dot4c_i32_i8_e32 v8, v41, v5
	v_dot4c_i32_i8_e32 v4, v43, v3
	v_add_u32_dpp v3, v56, v56 quad_perm:[1,0,3,2] row_mask:0xf bank_mask:0xf bound_ctrl:1
	v_add_u32_dpp v14, v20, v20 quad_perm:[1,0,3,2] row_mask:0xf bank_mask:0xf bound_ctrl:1
	v_add_u32_dpp v2, v2, v2 quad_perm:[2,3,0,1] row_mask:0xf bank_mask:0xf bound_ctrl:1
	v_add_u32_dpp v13, v13, v13 quad_perm:[2,3,0,1] row_mask:0xf bank_mask:0xf bound_ctrl:1
	v_add_u32_dpp v0, v0, v0 row_half_mirror row_mask:0xf bank_mask:0xf bound_ctrl:1
	v_add_u32_dpp v10, v10, v10 row_half_mirror row_mask:0xf bank_mask:0xf bound_ctrl:1
	v_add_u32_dpp v11, v11, v11 row_half_mirror row_mask:0xf bank_mask:0xf bound_ctrl:1
	v_add_u32_e32 v1, v16, v1
	v_dot4c_i32_i8_e32 v48, v43, v47
	v_dot4c_i32_i8_e32 v44, v42, v38
	v_dot4c_i32_i8_e32 v36, v41, v33
	v_dot4c_i32_i8_e32 v8, v42, v6
	v_add_u32_dpp v5, v52, v52 quad_perm:[1,0,3,2] row_mask:0xf bank_mask:0xf bound_ctrl:1
	v_add_u32_dpp v3, v3, v3 quad_perm:[2,3,0,1] row_mask:0xf bank_mask:0xf bound_ctrl:1
	v_add_u32_dpp v14, v14, v14 quad_perm:[2,3,0,1] row_mask:0xf bank_mask:0xf bound_ctrl:1
	v_add_u32_dpp v2, v2, v2 row_half_mirror row_mask:0xf bank_mask:0xf bound_ctrl:1
	v_add_u32_dpp v13, v13, v13 row_half_mirror row_mask:0xf bank_mask:0xf bound_ctrl:1
	v_cndmask_b32_e64 v0, v0, v1, s[12:13]
	v_cndmask_b32_e64 v1, v10, v11, s[12:13]
	v_dot4c_i32_i8_e32 v44, v43, v39
	v_dot4c_i32_i8_e32 v36, v42, v34
	v_dot4c_i32_i8_e32 v8, v43, v7
	v_add_u32_dpp v6, v48, v48 quad_perm:[1,0,3,2] row_mask:0xf bank_mask:0xf bound_ctrl:1
	v_add_u32_dpp v12, v12, v12 quad_perm:[1,0,3,2] row_mask:0xf bank_mask:0xf bound_ctrl:1
	v_add_u32_dpp v5, v5, v5 quad_perm:[2,3,0,1] row_mask:0xf bank_mask:0xf bound_ctrl:1
	v_add_u32_dpp v15, v15, v15 quad_perm:[2,3,0,1] row_mask:0xf bank_mask:0xf bound_ctrl:1
	v_add_u32_dpp v3, v3, v3 row_half_mirror row_mask:0xf bank_mask:0xf bound_ctrl:1
	v_add_u32_dpp v14, v14, v14 row_half_mirror row_mask:0xf bank_mask:0xf bound_ctrl:1
	v_cndmask_b32_e64 v0, v0, v2, s[14:15]
	v_cndmask_b32_e64 v1, v1, v13, s[14:15]
	v_dot4c_i32_i8_e32 v36, v43, v35
	v_add_u32_dpp v7, v44, v44 quad_perm:[1,0,3,2] row_mask:0xf bank_mask:0xf bound_ctrl:1
	v_add_u32_dpp v8, v8, v8 quad_perm:[1,0,3,2] row_mask:0xf bank_mask:0xf bound_ctrl:1
	v_add_u32_dpp v6, v6, v6 quad_perm:[2,3,0,1] row_mask:0xf bank_mask:0xf bound_ctrl:1
	v_add_u32_dpp v12, v12, v12 quad_perm:[2,3,0,1] row_mask:0xf bank_mask:0xf bound_ctrl:1
	v_add_u32_dpp v5, v5, v5 row_half_mirror row_mask:0xf bank_mask:0xf bound_ctrl:1
	v_add_u32_dpp v15, v15, v15 row_half_mirror row_mask:0xf bank_mask:0xf bound_ctrl:1
	v_cndmask_b32_e64 v0, v0, v3, s[16:17]
	v_cndmask_b32_e64 v1, v1, v14, s[16:17]
	v_add_u32_dpp v9, v36, v36 quad_perm:[1,0,3,2] row_mask:0xf bank_mask:0xf bound_ctrl:1
	v_add_u32_dpp v4, v4, v4 quad_perm:[1,0,3,2] row_mask:0xf bank_mask:0xf bound_ctrl:1
	v_add_u32_dpp v7, v7, v7 quad_perm:[2,3,0,1] row_mask:0xf bank_mask:0xf bound_ctrl:1
	v_add_u32_dpp v8, v8, v8 quad_perm:[2,3,0,1] row_mask:0xf bank_mask:0xf bound_ctrl:1
	v_add_u32_dpp v6, v6, v6 row_half_mirror row_mask:0xf bank_mask:0xf bound_ctrl:1
	v_add_u32_dpp v12, v12, v12 row_half_mirror row_mask:0xf bank_mask:0xf bound_ctrl:1
	v_cndmask_b32_e64 v0, v0, v5, s[18:19]
	v_cndmask_b32_e64 v1, v1, v15, s[18:19]
	s_lshl_b32 s78, s50, 9
	v_add_u32_dpp v9, v9, v9 quad_perm:[2,3,0,1] row_mask:0xf bank_mask:0xf bound_ctrl:1
	v_add_u32_dpp v4, v4, v4 quad_perm:[2,3,0,1] row_mask:0xf bank_mask:0xf bound_ctrl:1
	v_add_u32_dpp v7, v7, v7 row_half_mirror row_mask:0xf bank_mask:0xf bound_ctrl:1
	v_add_u32_dpp v8, v8, v8 row_half_mirror row_mask:0xf bank_mask:0xf bound_ctrl:1
	v_cndmask_b32_e64 v0, v0, v6, s[20:21]
	v_cndmask_b32_e64 v1, v1, v12, s[20:21]
	s_cmp_gt_u32 s76, 15
	v_add_u32_dpp v9, v9, v9 row_half_mirror row_mask:0xf bank_mask:0xf bound_ctrl:1
	v_add_u32_dpp v4, v4, v4 row_half_mirror row_mask:0xf bank_mask:0xf bound_ctrl:1
	v_cndmask_b32_e64 v0, v0, v7, s[22:23]
	v_cndmask_b32_e64 v1, v1, v8, s[22:23]
	s_cselect_b64 s[50:51], -1, 0
	v_cndmask_b32_e64 v0, v0, v9, s[24:25]
	v_cndmask_b32_e64 v1, v1, v4, s[24:25]
	s_mov_b64 s[52:53], -1
	s_and_b64 vcc, exec, s[50:51]
	v_add_u32_e32 v2, s78, v186
	s_cbranch_vccz .LBB0_1381
	ds_add_u32 v2, v0
	ds_add_u32 v2, v1 offset:32
	s_mov_b64 s[52:53], 0

.LBB0_1383:
	s_lshr_b32 s77, s77, 4
	s_lshl_b32 s40, s40, 10
	v_lshl_add_u64 v[40:41], v[144:145], 0, s[40:41]
	s_lshl_b32 s40, s77, 7
	v_lshl_add_u64 v[40:41], v[40:41], 0, s[40:41]
	global_load_dwordx4 v[40:43], v[40:41], off
	s_lshl_b32 s52, s77, 21
	s_add_u32 s52, s26, s52
	s_addc_u32 s53, s27, 0
	s_min_u32 s76, s76, 0x7c
	s_waitcnt lgkmcnt(1)
	v_mad_u32_u16 v0, v140, s81, v150
	v_mad_u32_u16 v1, v140, s81, v150 op_sel:[1,0,0,0]
	global_load_dwordx4 v[64:67], v0, s[52:53]
	global_load_dwordx4 v[60:63], v1, s[52:53]
	v_mad_u32_u16 v0, v141, s81, v150
	v_mad_u32_u16 v1, v141, s81, v150 op_sel:[1,0,0,0]
	global_load_dwordx4 v[56:59], v0, s[52:53]
	global_load_dwordx4 v[52:55], v1, s[52:53]
	v_mad_u32_u16 v0, v142, s81, v150
	v_mad_u32_u16 v1, v142, s81, v150 op_sel:[1,0,0,0]
	global_load_dwordx4 v[48:51], v0, s[52:53]
	global_load_dwordx4 v[44:47], v1, s[52:53]
	v_mad_u32_u16 v0, v143, s81, v150
	v_mad_u32_u16 v1, v143, s81, v150 op_sel:[1,0,0,0]
	global_load_dwordx4 v[36:39], v0, s[52:53]
	global_load_dwordx4 v[32:35], v1, s[52:53]
	s_waitcnt lgkmcnt(0)
	v_mad_u32_u16 v0, v136, s81, v150
	v_mad_u32_u16 v1, v136, s81, v150 op_sel:[1,0,0,0]
	global_load_dwordx4 v[28:31], v0, s[52:53]
	global_load_dwordx4 v[24:27], v1, s[52:53]
	v_mad_u32_u16 v0, v137, s81, v150
	v_mad_u32_u16 v1, v137, s81, v150 op_sel:[1,0,0,0]
	global_load_dwordx4 v[20:23], v0, s[52:53]
	global_load_dwordx4 v[16:19], v1, s[52:53]
	v_mad_u32_u16 v0, v138, s81, v150
	v_mad_u32_u16 v1, v138, s81, v150 op_sel:[1,0,0,0]
	global_load_dwordx4 v[12:15], v0, s[52:53]
	global_load_dwordx4 v[8:11], v1, s[52:53]
	v_mad_u32_u16 v0, v139, s81, v150
	v_mad_u32_u16 v1, v139, s81, v150 op_sel:[1,0,0,0]
	global_load_dwordx4 v[4:7], v0, s[52:53]
	s_nop 0
	global_load_dwordx4 v[0:3], v1, s[52:53]
	s_lshl_b32 s40, s76, 7
	s_addk_i32 s40, 0x180
	s_and_b32 s40, s40, 0x780
	v_lshl_add_u32 v136, s40, 1, v185
	ds_read_b128 v[140:143], v136
	ds_read_b128 v[136:139], v136 offset:16
	v_mov_b32_e32 v146, 0
	s_waitcnt vmcnt(32)
	v_dot4c_i32_i8_e32 v146, v80, v132
	v_mov_b32_e32 v132, 0
	s_waitcnt vmcnt(31)
	v_dot4c_i32_i8_e32 v132, v80, v128
	v_mov_b32_e32 v128, 0
	s_waitcnt vmcnt(30)
	v_dot4c_i32_i8_e32 v128, v80, v124
	v_mov_b32_e32 v124, 0
	s_waitcnt vmcnt(29)
	v_dot4c_i32_i8_e32 v124, v80, v120
	v_mov_b32_e32 v120, 0
	s_waitcnt vmcnt(28)
	v_dot4c_i32_i8_e32 v120, v80, v116
	v_mov_b32_e32 v116, 0
	s_waitcnt vmcnt(27)
	v_dot4c_i32_i8_e32 v116, v80, v112
	v_mov_b32_e32 v112, 0
	s_waitcnt vmcnt(26)
	v_dot4c_i32_i8_e32 v112, v80, v108
	v_mov_b32_e32 v108, 0
	s_waitcnt vmcnt(25)
	v_dot4c_i32_i8_e32 v108, v80, v104
	v_mov_b32_e32 v104, 0
	s_waitcnt vmcnt(24)
	v_dot4c_i32_i8_e32 v104, v80, v100
	v_mov_b32_e32 v100, 0
	s_waitcnt vmcnt(23)
	v_dot4c_i32_i8_e32 v100, v80, v96
	v_mov_b32_e32 v96, 0
	s_waitcnt vmcnt(22)
	v_dot4c_i32_i8_e32 v96, v80, v92
	v_mov_b32_e32 v92, 0
	s_waitcnt vmcnt(21)
	v_dot4c_i32_i8_e32 v92, v80, v88
	v_mov_b32_e32 v88, 0
	s_waitcnt vmcnt(20)
	v_dot4c_i32_i8_e32 v88, v80, v84
	v_mov_b32_e32 v84, 0
	v_dot4c_i32_i8_e32 v132, v81, v129
	s_waitcnt vmcnt(19)
	v_dot4c_i32_i8_e32 v84, v80, v76
	v_mov_b32_e32 v76, 0
	v_dot4c_i32_i8_e32 v146, v81, v133
	v_dot4c_i32_i8_e32 v132, v82, v130
	v_dot4c_i32_i8_e32 v104, v81, v101
	v_dot4c_i32_i8_e32 v100, v81, v97
	s_waitcnt vmcnt(18)
	v_dot4c_i32_i8_e32 v76, v80, v72
	v_mov_b32_e32 v72, 0
	v_dot4c_i32_i8_e32 v146, v82, v134
	v_dot4c_i32_i8_e32 v132, v83, v131
	v_dot4c_i32_i8_e32 v128, v81, v125
	v_dot4c_i32_i8_e32 v104, v82, v102
	v_dot4c_i32_i8_e32 v100, v82, v98
	v_dot4c_i32_i8_e32 v96, v81, v93
	v_dot4c_i32_i8_e32 v84, v81, v77
	s_waitcnt vmcnt(17)
	v_dot4c_i32_i8_e32 v72, v80, v68
	v_dot4c_i32_i8_e32 v146, v83, v135
	v_dot4c_i32_i8_e32 v128, v82, v126
	v_dot4c_i32_i8_e32 v124, v81, v121
	v_dot4c_i32_i8_e32 v120, v81, v117
	v_dot4c_i32_i8_e32 v116, v81, v113
	v_dot4c_i32_i8_e32 v112, v81, v109
	v_dot4c_i32_i8_e32 v108, v81, v105
	v_dot4c_i32_i8_e32 v104, v83, v103
	v_dot4c_i32_i8_e32 v100, v83, v99
	v_dot4c_i32_i8_e32 v96, v82, v94
	v_dot4c_i32_i8_e32 v92, v81, v89
	v_dot4c_i32_i8_e32 v88, v81, v85
	v_dot4c_i32_i8_e32 v84, v82, v78
	v_dot4c_i32_i8_e32 v76, v81, v73
	v_dot4c_i32_i8_e32 v72, v81, v69
	v_add_u32_dpp v69, v132, v132 quad_perm:[1,0,3,2] row_mask:0xf bank_mask:0xf bound_ctrl:1
	v_dot4c_i32_i8_e32 v128, v83, v127
	v_dot4c_i32_i8_e32 v124, v82, v122
	v_dot4c_i32_i8_e32 v120, v82, v118
	v_dot4c_i32_i8_e32 v116, v82, v114
	v_dot4c_i32_i8_e32 v112, v82, v110
	v_dot4c_i32_i8_e32 v108, v82, v106
	v_dot4c_i32_i8_e32 v96, v83, v95
	v_dot4c_i32_i8_e32 v92, v82, v90
	v_dot4c_i32_i8_e32 v88, v82, v86
	v_dot4c_i32_i8_e32 v84, v83, v79
	v_dot4c_i32_i8_e32 v76, v82, v74
	v_dot4c_i32_i8_e32 v72, v82, v70
	v_add_u32_dpp v68, v146, v146 quad_perm:[1,0,3,2] row_mask:0xf bank_mask:0xf bound_ctrl:1
	v_add_u32_dpp v78, v104, v104 quad_perm:[1,0,3,2] row_mask:0xf bank_mask:0xf bound_ctrl:1
	v_add_u32_dpp v79, v100, v100 quad_perm:[1,0,3,2] row_mask:0xf bank_mask:0xf bound_ctrl:1
	v_add_u32_dpp v69, v69, v69 quad_perm:[2,3,0,1] row_mask:0xf bank_mask:0xf bound_ctrl:1
	v_dot4c_i32_i8_e32 v124, v83, v123
	v_dot4c_i32_i8_e32 v120, v83, v119
	v_dot4c_i32_i8_e32 v116, v83, v115
	v_dot4c_i32_i8_e32 v112, v83, v111
	v_dot4c_i32_i8_e32 v108, v83, v107
	v_dot4c_i32_i8_e32 v92, v83, v91
	v_dot4c_i32_i8_e32 v88, v83, v87
	v_dot4c_i32_i8_e32 v76, v83, v75
	v_dot4c_i32_i8_e32 v72, v83, v71
	v_add_u32_dpp v70, v128, v128 quad_perm:[1,0,3,2] row_mask:0xf bank_mask:0xf bound_ctrl:1
	v_add_u32_dpp v80, v96, v96 quad_perm:[1,0,3,2] row_mask:0xf bank_mask:0xf bound_ctrl:1
	v_add_u32_dpp v83, v84, v84 quad_perm:[1,0,3,2] row_mask:0xf bank_mask:0xf bound_ctrl:1
	v_add_u32_dpp v68, v68, v68 quad_perm:[2,3,0,1] row_mask:0xf bank_mask:0xf bound_ctrl:1
	v_add_u32_dpp v78, v78, v78 quad_perm:[2,3,0,1] row_mask:0xf bank_mask:0xf bound_ctrl:1
	v_add_u32_dpp v79, v79, v79 quad_perm:[2,3,0,1] row_mask:0xf bank_mask:0xf bound_ctrl:1
	v_mov_b32_dpp v84, v69 row_half_mirror row_mask:0xf bank_mask:0xf bound_ctrl:1
	v_add_u32_dpp v71, v124, v124 quad_perm:[1,0,3,2] row_mask:0xf bank_mask:0xf bound_ctrl:1
	v_add_u32_dpp v81, v92, v92 quad_perm:[1,0,3,2] row_mask:0xf bank_mask:0xf bound_ctrl:1
	v_add_u32_dpp v70, v70, v70 quad_perm:[2,3,0,1] row_mask:0xf bank_mask:0xf bound_ctrl:1
	v_add_u32_dpp v80, v80, v80 quad_perm:[2,3,0,1] row_mask:0xf bank_mask:0xf bound_ctrl:1
	v_add_u32_dpp v68, v68, v68 row_half_mirror row_mask:0xf bank_mask:0xf bound_ctrl:1
	v_add_u32_dpp v78, v78, v78 row_half_mirror row_mask:0xf bank_mask:0xf bound_ctrl:1
	v_add_u32_dpp v79, v79, v79 row_half_mirror row_mask:0xf bank_mask:0xf bound_ctrl:1
	v_add_u32_e32 v69, v84, v69
	v_add_u32_dpp v73, v120, v120 quad_perm:[1,0,3,2] row_mask:0xf bank_mask:0xf bound_ctrl:1
	v_add_u32_dpp v82, v88, v88 quad_perm:[1,0,3,2] row_mask:0xf bank_mask:0xf bound_ctrl:1
	v_add_u32_dpp v71, v71, v71 quad_perm:[2,3,0,1] row_mask:0xf bank_mask:0xf bound_ctrl:1
	v_add_u32_dpp v81, v81, v81 quad_perm:[2,3,0,1] row_mask:0xf bank_mask:0xf bound_ctrl:1
	v_add_u32_dpp v70, v70, v70 row_half_mirror row_mask:0xf bank_mask:0xf bound_ctrl:1
	v_add_u32_dpp v80, v80, v80 row_half_mirror row_mask:0xf bank_mask:0xf bound_ctrl:1
	v_cndmask_b32_e64 v68, v68, v69, s[12:13]
	v_cndmask_b32_e64 v69, v78, v79, s[12:13]
	v_add_u32_dpp v74, v116, v116 quad_perm:[1,0,3,2] row_mask:0xf bank_mask:0xf bound_ctrl:1
	v_add_u32_dpp v73, v73, v73 quad_perm:[2,3,0,1] row_mask:0xf bank_mask:0xf bound_ctrl:1
	v_add_u32_dpp v82, v82, v82 quad_perm:[2,3,0,1] row_mask:0xf bank_mask:0xf bound_ctrl:1
	v_add_u32_dpp v71, v71, v71 row_half_mirror row_mask:0xf bank_mask:0xf bound_ctrl:1
	v_add_u32_dpp v81, v81, v81 row_half_mirror row_mask:0xf bank_mask:0xf bound_ctrl:1
	v_cndmask_b32_e64 v68, v68, v70, s[14:15]
	v_cndmask_b32_e64 v69, v69, v80, s[14:15]
	v_add_u32_dpp v75, v112, v112 quad_perm:[1,0,3,2] row_mask:0xf bank_mask:0xf bound_ctrl:1
	v_add_u32_dpp v76, v76, v76 quad_perm:[1,0,3,2] row_mask:0xf bank_mask:0xf bound_ctrl:1
	v_add_u32_dpp v74, v74, v74 quad_perm:[2,3,0,1] row_mask:0xf bank_mask:0xf bound_ctrl:1
	v_add_u32_dpp v83, v83, v83 quad_perm:[2,3,0,1] row_mask:0xf bank_mask:0xf bound_ctrl:1
	v_add_u32_dpp v73, v73, v73 row_half_mirror row_mask:0xf bank_mask:0xf bound_ctrl:1
	v_add_u32_dpp v82, v82, v82 row_half_mirror row_mask:0xf bank_mask:0xf bound_ctrl:1
	v_cndmask_b32_e64 v68, v68, v71, s[16:17]
	v_cndmask_b32_e64 v69, v69, v81, s[16:17]
	v_add_u32_dpp v77, v108, v108 quad_perm:[1,0,3,2] row_mask:0xf bank_mask:0xf bound_ctrl:1
	v_add_u32_dpp v72, v72, v72 quad_perm:[1,0,3,2] row_mask:0xf bank_mask:0xf bound_ctrl:1
	v_add_u32_dpp v75, v75, v75 quad_perm:[2,3,0,1] row_mask:0xf bank_mask:0xf bound_ctrl:1
	v_add_u32_dpp v76, v76, v76 quad_perm:[2,3,0,1] row_mask:0xf bank_mask:0xf bound_ctrl:1
	v_add_u32_dpp v74, v74, v74 row_half_mirror row_mask:0xf bank_mask:0xf bound_ctrl:1
	v_add_u32_dpp v83, v83, v83 row_half_mirror row_mask:0xf bank_mask:0xf bound_ctrl:1
	v_cndmask_b32_e64 v68, v68, v73, s[18:19]
	v_cndmask_b32_e64 v69, v69, v82, s[18:19]
	v_add_u32_dpp v77, v77, v77 quad_perm:[2,3,0,1] row_mask:0xf bank_mask:0xf bound_ctrl:1
	v_add_u32_dpp v72, v72, v72 quad_perm:[2,3,0,1] row_mask:0xf bank_mask:0xf bound_ctrl:1
	v_add_u32_dpp v75, v75, v75 row_half_mirror row_mask:0xf bank_mask:0xf bound_ctrl:1
	v_add_u32_dpp v76, v76, v76 row_half_mirror row_mask:0xf bank_mask:0xf bound_ctrl:1
	v_cndmask_b32_e64 v68, v68, v74, s[20:21]
	v_cndmask_b32_e64 v69, v69, v83, s[20:21]
	v_add_u32_dpp v77, v77, v77 row_half_mirror row_mask:0xf bank_mask:0xf bound_ctrl:1
	v_add_u32_dpp v72, v72, v72 row_half_mirror row_mask:0xf bank_mask:0xf bound_ctrl:1
	v_cndmask_b32_e64 v68, v68, v75, s[22:23]
	v_cndmask_b32_e64 v69, v69, v76, s[22:23]
	s_lshl_b32 s40, s45, 9
	v_cndmask_b32_e64 v68, v68, v77, s[24:25]
	v_cndmask_b32_e64 v69, v69, v72, s[24:25]
	s_mov_b64 s[52:53], -1
	s_and_b64 vcc, exec, s[50:51]
	v_add_u32_e32 v70, s40, v186
	s_cbranch_vccz .LBB0_1385
	ds_add_u32 v70, v68
	ds_add_u32 v70, v69 offset:32
	s_mov_b64 s[52:53], 0

.LBB0_1387:
	s_mov_b32 s33, 0
	s_waitcnt vmcnt(0)
	v_mov_b32_e32 v0, v206
	v_mov_b32_e32 v1, v205
	v_mov_b32_e32 v2, v204
	s_mov_b32 s40, s61
	s_branch .LBB0_1389
